# finish(): xor-1 lane exchange via DPP quad_perm instead of ds_bpermute+lgkmcnt(0) (32 per unit tail), on top of gate-word preload
# baseline (speedup 1.0000x reference)
.LBB0_1021:
	s_and_saveexec_b64 s[48:49], s[44:45]
	ds_write_b32 v181, v81
	s_or_b64 exec, exec, s[48:49]
	s_waitcnt lgkmcnt(0)
	v_lshl_add_u32 v68, v167, 4, s41
	ds_read_b128 v[70:73], v68
	s_ashr_i32 s47, s46, 31
	s_lshl_b64 s[16:17], s[46:47], 11
	v_readlane_b32 s1, v253, 51
	s_add_u32 s1, s1, s16
	v_readlane_b32 s9, v253, 52
	s_waitcnt lgkmcnt(0)
	v_rcp_f32_e32 v69, v70
	v_rcp_f32_e32 v70, v71
	s_addc_u32 s9, s9, s17
	s_add_u32 s1, s1, s78
	v_and_b32_e32 v1, 1, v164
	s_addc_u32 s9, s9, 0
	s_lshl_b32 s13, s36, 1
	v_cmp_eq_u32_e32 vcc, 0, v1
	v_and_b32_e32 v2, 30, v164
	v_lshlrev_b32_e32 v71, 12, v167
	v_lshlrev_b32_e32 v1, 10, v1
	s_add_u32 s44, s1, s13
	v_or3_b32 v1, v71, v1, v2
	v_mul_f32_e32 v2, v52, v69
	v_mul_f32_e32 v52, v53, v70
	s_addc_u32 s45, s9, 0
	v_readlane_b32 s1, v253, 53
	v_cndmask_b32_e32 v53, v2, v52, vcc
	s_add_u32 s1, s1, s16
	v_readlane_b32 s9, v253, 54
	s_nop 1
	v_mov_b32_dpp v53, v53 quad_perm:[1,0,3,2] row_mask:0xf bank_mask:0xf
	s_addc_u32 s9, s9, s17
	s_add_u32 s1, s1, s78
	s_addc_u32 s9, s9, 0
	s_add_u32 s46, s1, s13
	s_addc_u32 s47, s9, 0
	v_cndmask_b32_e32 v71, v53, v2, vcc
	v_lshlrev_b32_e32 v2, 1, v1
	v_or_b32_e32 v74, 0x1000, v2
	v_or_b32_e32 v75, 0x4000, v2
	v_or_b32_e32 v76, 0x5000, v2
	v_or_b32_e32 v77, 0x8000, v2
	v_or_b32_e32 v78, 0x9000, v2
	v_or_b32_e32 v79, 0xc000, v2
	v_or_b32_e32 v80, 0xd000, v2
	global_load_dword v81, v2, s[46:47]
	global_load_dword v82, v2, s[46:47] offset:64
	global_load_dword v83, v2, s[46:47] offset:128
	global_load_dword v84, v2, s[46:47] offset:192
	global_load_dword v85, v74, s[46:47]
	global_load_dword v86, v74, s[46:47] offset:64
	global_load_dword v87, v74, s[46:47] offset:128
	global_load_dword v88, v74, s[46:47] offset:192
	global_load_dword v89, v75, s[46:47]
	global_load_dword v90, v75, s[46:47] offset:64
	global_load_dword v91, v75, s[46:47] offset:128
	global_load_dword v92, v75, s[46:47] offset:192
	global_load_dword v93, v76, s[46:47]
	global_load_dword v94, v76, s[46:47] offset:64
	global_load_dword v95, v76, s[46:47] offset:128
	global_load_dword v96, v76, s[46:47] offset:192
	global_load_dword v97, v77, s[46:47]
	global_load_dword v98, v77, s[46:47] offset:64
	global_load_dword v99, v77, s[46:47] offset:128
	global_load_dword v100, v77, s[46:47] offset:192
	global_load_dword v101, v78, s[46:47]
	global_load_dword v102, v78, s[46:47] offset:64
	global_load_dword v103, v78, s[46:47] offset:128
	global_load_dword v104, v78, s[46:47] offset:192
	global_load_dword v105, v79, s[46:47]
	global_load_dword v106, v79, s[46:47] offset:64
	global_load_dword v107, v79, s[46:47] offset:128
	global_load_dword v108, v79, s[46:47] offset:192
	global_load_dword v109, v80, s[46:47]
	global_load_dword v110, v80, s[46:47] offset:64
	global_load_dword v111, v80, s[46:47] offset:128
	global_load_dword v112, v80, s[46:47] offset:192
	s_nop 0
	s_nop 0
	v_cndmask_b32_e32 v52, v52, v53, vcc
	s_waitcnt vmcnt(31)
	v_lshlrev_b32_e32 v53, 16, v81
	v_and_b32_e32 v1, 0xffff0000, v81
	v_mul_f32_e32 v53, v71, v53
	v_mul_f32_e32 v1, v52, v1
	v_cvt_pk_bf16_f32 v1, v53, v1
	global_store_dword v2, v1, s[44:45]
	v_mul_f32_e32 v1, v36, v69
	v_mul_f32_e32 v36, v37, v70
	v_cndmask_b32_e32 v37, v1, v36, vcc
	s_nop 1
	v_mov_b32_dpp v37, v37 quad_perm:[1,0,3,2] row_mask:0xf bank_mask:0xf
	v_cndmask_b32_e32 v1, v37, v1, vcc
	v_cndmask_b32_e32 v36, v36, v37, vcc
	s_waitcnt vmcnt(31)
	v_lshlrev_b32_e32 v52, 16, v82
	v_and_b32_e32 v37, 0xffff0000, v82
	v_mul_f32_e32 v1, v1, v52
	v_mul_f32_e32 v36, v36, v37
	v_cvt_pk_bf16_f32 v1, v1, v36
	global_store_dword v2, v1, s[44:45] offset:64
	v_mul_f32_e32 v1, v20, v69
	v_mul_f32_e32 v20, v21, v70
	v_cndmask_b32_e32 v21, v1, v20, vcc
	s_nop 1
	v_mov_b32_dpp v21, v21 quad_perm:[1,0,3,2] row_mask:0xf bank_mask:0xf
	v_cndmask_b32_e32 v1, v21, v1, vcc
	v_cndmask_b32_e32 v20, v20, v21, vcc
	s_waitcnt vmcnt(31)
	v_lshlrev_b32_e32 v36, 16, v83
	v_and_b32_e32 v21, 0xffff0000, v83
	v_mul_f32_e32 v1, v1, v36
	v_mul_f32_e32 v20, v20, v21
	v_cvt_pk_bf16_f32 v1, v1, v20
	global_store_dword v2, v1, s[44:45] offset:128
	v_mul_f32_e32 v1, v4, v69
	v_mul_f32_e32 v4, v5, v70
	v_cndmask_b32_e32 v5, v1, v4, vcc
	s_nop 1
	v_mov_b32_dpp v5, v5 quad_perm:[1,0,3,2] row_mask:0xf bank_mask:0xf
	v_cndmask_b32_e32 v1, v5, v1, vcc
	v_cndmask_b32_e32 v4, v4, v5, vcc
	s_waitcnt vmcnt(31)
	v_lshlrev_b32_e32 v20, 16, v84
	v_and_b32_e32 v5, 0xffff0000, v84
	v_mul_f32_e32 v1, v1, v20
	v_mul_f32_e32 v4, v4, v5
	v_cvt_pk_bf16_f32 v1, v1, v4
	global_store_dword v2, v1, s[44:45] offset:192
	v_rcp_f32_e32 v1, v72
	v_rcp_f32_e32 v4, v73
	v_mul_f32_e32 v5, v54, v1
	v_mul_f32_e32 v20, v55, v4
	v_cndmask_b32_e32 v21, v5, v20, vcc
	s_nop 1
	v_mov_b32_dpp v21, v21 quad_perm:[1,0,3,2] row_mask:0xf bank_mask:0xf
	v_cndmask_b32_e32 v5, v21, v5, vcc
	v_cndmask_b32_e32 v20, v20, v21, vcc
	v_or_b32_e32 v21, 0x1000, v2
	s_waitcnt vmcnt(31)
	v_lshlrev_b32_e32 v37, 16, v85
	v_and_b32_e32 v36, 0xffff0000, v85
	v_mul_f32_e32 v5, v5, v37
	v_mul_f32_e32 v20, v20, v36
	v_cvt_pk_bf16_f32 v5, v5, v20
	global_store_dword v21, v5, s[44:45]
	v_mul_f32_e32 v5, v38, v1
	v_mul_f32_e32 v20, v39, v4
	v_cndmask_b32_e32 v36, v5, v20, vcc
	s_nop 1
	v_mov_b32_dpp v36, v36 quad_perm:[1,0,3,2] row_mask:0xf bank_mask:0xf
	v_cndmask_b32_e32 v5, v36, v5, vcc
	v_cndmask_b32_e32 v20, v20, v36, vcc
	s_waitcnt vmcnt(31)
	v_lshlrev_b32_e32 v37, 16, v86
	v_and_b32_e32 v36, 0xffff0000, v86
	v_mul_f32_e32 v5, v5, v37
	v_mul_f32_e32 v20, v20, v36
	v_cvt_pk_bf16_f32 v5, v5, v20
	global_store_dword v21, v5, s[44:45] offset:64
	v_mul_f32_e32 v5, v22, v1
	v_mul_f32_e32 v20, v23, v4
	v_cndmask_b32_e32 v22, v5, v20, vcc
	s_nop 1
	v_mov_b32_dpp v22, v22 quad_perm:[1,0,3,2] row_mask:0xf bank_mask:0xf
	v_mul_f32_e32 v1, v6, v1
	v_mul_f32_e32 v4, v7, v4
	v_cndmask_b32_e32 v5, v22, v5, vcc
	v_cndmask_b32_e32 v20, v20, v22, vcc
	s_waitcnt vmcnt(31)
	v_lshlrev_b32_e32 v23, 16, v87
	v_and_b32_e32 v22, 0xffff0000, v87
	v_mul_f32_e32 v5, v5, v23
	v_mul_f32_e32 v20, v20, v22
	v_cvt_pk_bf16_f32 v5, v5, v20
	global_store_dword v21, v5, s[44:45] offset:128
	v_cndmask_b32_e32 v5, v1, v4, vcc
	s_nop 1
	v_mov_b32_dpp v5, v5 quad_perm:[1,0,3,2] row_mask:0xf bank_mask:0xf
	v_cndmask_b32_e32 v1, v5, v1, vcc
	v_cndmask_b32_e32 v4, v4, v5, vcc
	s_waitcnt vmcnt(31)
	v_lshlrev_b32_e32 v6, 16, v88
	v_and_b32_e32 v5, 0xffff0000, v88
	v_mul_f32_e32 v1, v1, v6
	v_mul_f32_e32 v4, v4, v5
	v_cvt_pk_bf16_f32 v1, v1, v4
	ds_read_b128 v[4:7], v68 offset:32
	global_store_dword v21, v1, s[44:45] offset:192
	s_waitcnt lgkmcnt(0)
	v_rcp_f32_e32 v4, v4
	v_rcp_f32_e32 v5, v5
	v_mul_f32_e32 v1, v56, v4
	v_mul_f32_e32 v20, v57, v5
	v_cndmask_b32_e32 v21, v1, v20, vcc
	s_nop 1
	v_mov_b32_dpp v21, v21 quad_perm:[1,0,3,2] row_mask:0xf bank_mask:0xf
	v_cndmask_b32_e32 v1, v21, v1, vcc
	v_cndmask_b32_e32 v20, v20, v21, vcc
	v_or_b32_e32 v21, 0x4000, v2
	s_waitcnt vmcnt(31)
	v_lshlrev_b32_e32 v23, 16, v89
	v_and_b32_e32 v22, 0xffff0000, v89
	v_mul_f32_e32 v1, v1, v23
	v_mul_f32_e32 v20, v20, v22
	v_cvt_pk_bf16_f32 v1, v1, v20
	global_store_dword v21, v1, s[44:45]
	v_mul_f32_e32 v1, v40, v4
	v_mul_f32_e32 v20, v41, v5
	v_cndmask_b32_e32 v22, v1, v20, vcc
	s_nop 1
	v_mov_b32_dpp v22, v22 quad_perm:[1,0,3,2] row_mask:0xf bank_mask:0xf
	v_cndmask_b32_e32 v1, v22, v1, vcc
	v_cndmask_b32_e32 v20, v20, v22, vcc
	s_waitcnt vmcnt(31)
	v_lshlrev_b32_e32 v23, 16, v90
	v_and_b32_e32 v22, 0xffff0000, v90
	v_mul_f32_e32 v1, v1, v23
	v_mul_f32_e32 v20, v20, v22
	v_cvt_pk_bf16_f32 v1, v1, v20
	global_store_dword v21, v1, s[44:45] offset:64
	v_mul_f32_e32 v1, v24, v4
	v_mul_f32_e32 v20, v25, v5
	v_cndmask_b32_e32 v22, v1, v20, vcc
	s_nop 1
	v_mov_b32_dpp v22, v22 quad_perm:[1,0,3,2] row_mask:0xf bank_mask:0xf
	v_cndmask_b32_e32 v1, v22, v1, vcc
	v_cndmask_b32_e32 v20, v20, v22, vcc
	s_waitcnt vmcnt(31)
	v_lshlrev_b32_e32 v23, 16, v91
	v_and_b32_e32 v22, 0xffff0000, v91
	v_mul_f32_e32 v1, v1, v23
	v_mul_f32_e32 v20, v20, v22
	v_cvt_pk_bf16_f32 v1, v1, v20
	global_store_dword v21, v1, s[44:45] offset:128
	v_mul_f32_e32 v1, v8, v4
	v_mul_f32_e32 v4, v9, v5
	v_cndmask_b32_e32 v5, v1, v4, vcc
	s_nop 1
	v_mov_b32_dpp v5, v5 quad_perm:[1,0,3,2] row_mask:0xf bank_mask:0xf
	v_cndmask_b32_e32 v1, v5, v1, vcc
	v_cndmask_b32_e32 v4, v4, v5, vcc
	s_waitcnt vmcnt(31)
	v_lshlrev_b32_e32 v8, 16, v92
	v_and_b32_e32 v5, 0xffff0000, v92
	v_mul_f32_e32 v1, v1, v8
	v_mul_f32_e32 v4, v4, v5
	v_cvt_pk_bf16_f32 v1, v1, v4
	global_store_dword v21, v1, s[44:45] offset:192
	v_rcp_f32_e32 v1, v6
	v_rcp_f32_e32 v4, v7
	v_mul_f32_e32 v5, v58, v1
	v_mul_f32_e32 v6, v59, v4
	v_cndmask_b32_e32 v7, v5, v6, vcc
	s_nop 1
	v_mov_b32_dpp v7, v7 quad_perm:[1,0,3,2] row_mask:0xf bank_mask:0xf
	v_cndmask_b32_e32 v5, v7, v5, vcc
	v_cndmask_b32_e32 v6, v6, v7, vcc
	v_or_b32_e32 v7, 0x5000, v2
	s_waitcnt vmcnt(31)
	v_lshlrev_b32_e32 v9, 16, v93
	v_and_b32_e32 v8, 0xffff0000, v93
	v_mul_f32_e32 v5, v5, v9
	v_mul_f32_e32 v6, v6, v8
	v_cvt_pk_bf16_f32 v5, v5, v6
	global_store_dword v7, v5, s[44:45]
	v_mul_f32_e32 v5, v42, v1
	v_mul_f32_e32 v6, v43, v4
	v_cndmask_b32_e32 v8, v5, v6, vcc
	s_nop 1
	v_mov_b32_dpp v8, v8 quad_perm:[1,0,3,2] row_mask:0xf bank_mask:0xf
	v_cndmask_b32_e32 v5, v8, v5, vcc
	v_cndmask_b32_e32 v6, v6, v8, vcc
	s_waitcnt vmcnt(31)
	v_lshlrev_b32_e32 v9, 16, v94
	v_and_b32_e32 v8, 0xffff0000, v94
	v_mul_f32_e32 v5, v5, v9
	v_mul_f32_e32 v6, v6, v8
	v_cvt_pk_bf16_f32 v5, v5, v6
	global_store_dword v7, v5, s[44:45] offset:64
	v_mul_f32_e32 v5, v26, v1
	v_mul_f32_e32 v6, v27, v4
	v_cndmask_b32_e32 v8, v5, v6, vcc
	s_nop 1
	v_mov_b32_dpp v8, v8 quad_perm:[1,0,3,2] row_mask:0xf bank_mask:0xf
	v_mul_f32_e32 v1, v10, v1
	v_mul_f32_e32 v4, v11, v4
	v_cndmask_b32_e32 v5, v8, v5, vcc
	v_cndmask_b32_e32 v6, v6, v8, vcc
	s_waitcnt vmcnt(31)
	v_lshlrev_b32_e32 v9, 16, v95
	v_and_b32_e32 v8, 0xffff0000, v95
	v_mul_f32_e32 v5, v5, v9
	v_mul_f32_e32 v6, v6, v8
	v_cvt_pk_bf16_f32 v5, v5, v6
	global_store_dword v7, v5, s[44:45] offset:128
	v_cndmask_b32_e32 v5, v1, v4, vcc
	s_nop 1
	v_mov_b32_dpp v5, v5 quad_perm:[1,0,3,2] row_mask:0xf bank_mask:0xf
	v_cndmask_b32_e32 v1, v5, v1, vcc
	v_cndmask_b32_e32 v4, v4, v5, vcc
	s_waitcnt vmcnt(31)
	v_lshlrev_b32_e32 v6, 16, v96
	v_and_b32_e32 v5, 0xffff0000, v96
	v_mul_f32_e32 v1, v1, v6
	v_mul_f32_e32 v4, v4, v5
	v_cvt_pk_bf16_f32 v1, v1, v4
	global_store_dword v7, v1, s[44:45] offset:192
	ds_read_b128 v[4:7], v68 offset:64
	s_waitcnt lgkmcnt(0)
	v_rcp_f32_e32 v1, v4
	v_rcp_f32_e32 v4, v5
	v_mul_f32_e32 v5, v60, v1
	v_mul_f32_e32 v8, v61, v4
	v_cndmask_b32_e32 v9, v5, v8, vcc
	s_nop 1
	v_mov_b32_dpp v9, v9 quad_perm:[1,0,3,2] row_mask:0xf bank_mask:0xf
	v_cndmask_b32_e32 v5, v9, v5, vcc
	v_cndmask_b32_e32 v8, v8, v9, vcc
	v_or_b32_e32 v9, 0x8000, v2
	s_waitcnt vmcnt(31)
	v_lshlrev_b32_e32 v11, 16, v97
	v_and_b32_e32 v10, 0xffff0000, v97
	v_mul_f32_e32 v5, v5, v11
	v_mul_f32_e32 v8, v8, v10
	v_cvt_pk_bf16_f32 v5, v5, v8
	global_store_dword v9, v5, s[44:45]
	v_mul_f32_e32 v5, v44, v1
	v_mul_f32_e32 v8, v45, v4
	v_cndmask_b32_e32 v10, v5, v8, vcc
	s_nop 1
	v_mov_b32_dpp v10, v10 quad_perm:[1,0,3,2] row_mask:0xf bank_mask:0xf
	v_cndmask_b32_e32 v5, v10, v5, vcc
	v_cndmask_b32_e32 v8, v8, v10, vcc
	s_waitcnt vmcnt(31)
	v_lshlrev_b32_e32 v11, 16, v98
	v_and_b32_e32 v10, 0xffff0000, v98
	v_mul_f32_e32 v5, v5, v11
	v_mul_f32_e32 v8, v8, v10
	v_cvt_pk_bf16_f32 v5, v5, v8
	global_store_dword v9, v5, s[44:45] offset:64
	v_mul_f32_e32 v5, v28, v1
	v_mul_f32_e32 v8, v29, v4
	v_cndmask_b32_e32 v10, v5, v8, vcc
	s_nop 1
	v_mov_b32_dpp v10, v10 quad_perm:[1,0,3,2] row_mask:0xf bank_mask:0xf
	v_mul_f32_e32 v1, v12, v1
	v_mul_f32_e32 v4, v13, v4
	v_cndmask_b32_e32 v5, v10, v5, vcc
	v_cndmask_b32_e32 v8, v8, v10, vcc
	s_waitcnt vmcnt(31)
	v_lshlrev_b32_e32 v11, 16, v99
	v_and_b32_e32 v10, 0xffff0000, v99
	v_mul_f32_e32 v5, v5, v11
	v_mul_f32_e32 v8, v8, v10
	v_cvt_pk_bf16_f32 v5, v5, v8
	global_store_dword v9, v5, s[44:45] offset:128
	v_cndmask_b32_e32 v5, v1, v4, vcc
	s_nop 1
	v_mov_b32_dpp v5, v5 quad_perm:[1,0,3,2] row_mask:0xf bank_mask:0xf
	v_cndmask_b32_e32 v1, v5, v1, vcc
	v_cndmask_b32_e32 v4, v4, v5, vcc
	s_waitcnt vmcnt(31)
	v_lshlrev_b32_e32 v8, 16, v100
	v_and_b32_e32 v5, 0xffff0000, v100
	v_mul_f32_e32 v1, v1, v8
	v_mul_f32_e32 v4, v4, v5
	v_cvt_pk_bf16_f32 v1, v1, v4
	global_store_dword v9, v1, s[44:45] offset:192
	v_rcp_f32_e32 v1, v6
	v_rcp_f32_e32 v4, v7
	v_mul_f32_e32 v5, v62, v1
	v_mul_f32_e32 v6, v63, v4
	v_cndmask_b32_e32 v7, v5, v6, vcc
	s_nop 1
	v_mov_b32_dpp v7, v7 quad_perm:[1,0,3,2] row_mask:0xf bank_mask:0xf
	v_cndmask_b32_e32 v5, v7, v5, vcc
	v_cndmask_b32_e32 v6, v6, v7, vcc
	v_or_b32_e32 v7, 0x9000, v2
	s_waitcnt vmcnt(31)
	v_lshlrev_b32_e32 v9, 16, v101
	v_and_b32_e32 v8, 0xffff0000, v101
	v_mul_f32_e32 v5, v5, v9
	v_mul_f32_e32 v6, v6, v8
	v_cvt_pk_bf16_f32 v5, v5, v6
	global_store_dword v7, v5, s[44:45]
	v_mul_f32_e32 v5, v46, v1
	v_mul_f32_e32 v6, v47, v4
	v_cndmask_b32_e32 v8, v5, v6, vcc
	s_nop 1
	v_mov_b32_dpp v8, v8 quad_perm:[1,0,3,2] row_mask:0xf bank_mask:0xf
	v_cndmask_b32_e32 v5, v8, v5, vcc
	v_cndmask_b32_e32 v6, v6, v8, vcc
	s_waitcnt vmcnt(31)
	v_lshlrev_b32_e32 v9, 16, v102
	v_and_b32_e32 v8, 0xffff0000, v102
	v_mul_f32_e32 v5, v5, v9
	v_mul_f32_e32 v6, v6, v8
	v_cvt_pk_bf16_f32 v5, v5, v6
	global_store_dword v7, v5, s[44:45] offset:64
	v_mul_f32_e32 v5, v30, v1
	v_mul_f32_e32 v6, v31, v4
	v_cndmask_b32_e32 v8, v5, v6, vcc
	s_nop 1
	v_mov_b32_dpp v8, v8 quad_perm:[1,0,3,2] row_mask:0xf bank_mask:0xf
	v_mul_f32_e32 v1, v14, v1
	v_mul_f32_e32 v4, v15, v4
	v_cndmask_b32_e32 v5, v8, v5, vcc
	v_cndmask_b32_e32 v6, v6, v8, vcc
	s_waitcnt vmcnt(31)
	v_lshlrev_b32_e32 v9, 16, v103
	v_and_b32_e32 v8, 0xffff0000, v103
	v_mul_f32_e32 v5, v5, v9
	v_mul_f32_e32 v6, v6, v8
	v_cvt_pk_bf16_f32 v5, v5, v6
	global_store_dword v7, v5, s[44:45] offset:128
	v_cndmask_b32_e32 v5, v1, v4, vcc
	s_nop 1
	v_mov_b32_dpp v5, v5 quad_perm:[1,0,3,2] row_mask:0xf bank_mask:0xf
	v_cndmask_b32_e32 v1, v5, v1, vcc
	v_cndmask_b32_e32 v4, v4, v5, vcc
	s_waitcnt vmcnt(31)
	v_lshlrev_b32_e32 v6, 16, v104
	v_and_b32_e32 v5, 0xffff0000, v104
	v_mul_f32_e32 v1, v1, v6
	v_mul_f32_e32 v4, v4, v5
	v_cvt_pk_bf16_f32 v1, v1, v4
	global_store_dword v7, v1, s[44:45] offset:192
	ds_read_b128 v[4:7], v68 offset:96
	s_waitcnt lgkmcnt(0)
	v_rcp_f32_e32 v4, v4
	v_rcp_f32_e32 v5, v5
	v_mul_f32_e32 v1, v64, v4
	v_mul_f32_e32 v8, v65, v5
	v_cndmask_b32_e32 v9, v1, v8, vcc
	s_nop 1
	v_mov_b32_dpp v9, v9 quad_perm:[1,0,3,2] row_mask:0xf bank_mask:0xf
	v_cndmask_b32_e32 v1, v9, v1, vcc
	v_cndmask_b32_e32 v8, v8, v9, vcc
	v_or_b32_e32 v9, 0xc000, v2
	v_or_b32_e32 v2, 0xd000, v2
	s_waitcnt vmcnt(31)
	v_lshlrev_b32_e32 v11, 16, v105
	v_and_b32_e32 v10, 0xffff0000, v105
	v_mul_f32_e32 v1, v1, v11
	v_mul_f32_e32 v8, v8, v10
	v_cvt_pk_bf16_f32 v1, v1, v8
	global_store_dword v9, v1, s[44:45]
	v_mul_f32_e32 v1, v48, v4
	v_mul_f32_e32 v8, v49, v5
	v_cndmask_b32_e32 v10, v1, v8, vcc
	s_nop 1
	v_mov_b32_dpp v10, v10 quad_perm:[1,0,3,2] row_mask:0xf bank_mask:0xf
	v_cndmask_b32_e32 v1, v10, v1, vcc
	v_cndmask_b32_e32 v8, v8, v10, vcc
	s_waitcnt vmcnt(31)
	v_lshlrev_b32_e32 v11, 16, v106
	v_and_b32_e32 v10, 0xffff0000, v106
	v_mul_f32_e32 v1, v1, v11
	v_mul_f32_e32 v8, v8, v10
	v_cvt_pk_bf16_f32 v1, v1, v8
	global_store_dword v9, v1, s[44:45] offset:64
	v_mul_f32_e32 v1, v32, v4
	v_mul_f32_e32 v8, v33, v5
	v_cndmask_b32_e32 v10, v1, v8, vcc
	s_nop 1
	v_mov_b32_dpp v10, v10 quad_perm:[1,0,3,2] row_mask:0xf bank_mask:0xf
	v_cndmask_b32_e32 v1, v10, v1, vcc
	v_cndmask_b32_e32 v8, v8, v10, vcc
	s_waitcnt vmcnt(31)
	v_lshlrev_b32_e32 v11, 16, v107
	v_and_b32_e32 v10, 0xffff0000, v107
	v_mul_f32_e32 v1, v1, v11
	v_mul_f32_e32 v8, v8, v10
	v_cvt_pk_bf16_f32 v1, v1, v8
	global_store_dword v9, v1, s[44:45] offset:128
	v_mul_f32_e32 v1, v16, v4
	v_mul_f32_e32 v4, v17, v5
	v_cndmask_b32_e32 v5, v1, v4, vcc
	s_nop 1
	v_mov_b32_dpp v5, v5 quad_perm:[1,0,3,2] row_mask:0xf bank_mask:0xf
	v_cndmask_b32_e32 v1, v5, v1, vcc
	v_cndmask_b32_e32 v4, v4, v5, vcc
	s_waitcnt vmcnt(31)
	v_lshlrev_b32_e32 v8, 16, v108
	v_and_b32_e32 v5, 0xffff0000, v108
	v_mul_f32_e32 v1, v1, v8
	v_mul_f32_e32 v4, v4, v5
	v_cvt_pk_bf16_f32 v1, v1, v4
	global_store_dword v9, v1, s[44:45] offset:192
	v_rcp_f32_e32 v1, v6
	v_rcp_f32_e32 v4, v7
	v_mul_f32_e32 v5, v66, v1
	v_mul_f32_e32 v6, v67, v4
	v_cndmask_b32_e32 v7, v5, v6, vcc
	s_nop 1
	v_mov_b32_dpp v7, v7 quad_perm:[1,0,3,2] row_mask:0xf bank_mask:0xf
	v_cndmask_b32_e32 v5, v7, v5, vcc
	v_cndmask_b32_e32 v6, v6, v7, vcc
	s_waitcnt vmcnt(31)
	v_lshlrev_b32_e32 v8, 16, v109
	v_and_b32_e32 v7, 0xffff0000, v109
	v_mul_f32_e32 v5, v5, v8
	v_mul_f32_e32 v6, v6, v7
	v_cvt_pk_bf16_f32 v5, v5, v6
	global_store_dword v2, v5, s[44:45]
	v_mul_f32_e32 v5, v50, v1
	v_mul_f32_e32 v6, v51, v4
	v_cndmask_b32_e32 v7, v5, v6, vcc
	s_nop 1
	v_mov_b32_dpp v7, v7 quad_perm:[1,0,3,2] row_mask:0xf bank_mask:0xf
	v_cndmask_b32_e32 v5, v7, v5, vcc
	v_cndmask_b32_e32 v6, v6, v7, vcc
	s_waitcnt vmcnt(31)
	v_lshlrev_b32_e32 v8, 16, v110
	v_and_b32_e32 v7, 0xffff0000, v110
	v_mul_f32_e32 v5, v5, v8
	v_mul_f32_e32 v6, v6, v7
	v_cvt_pk_bf16_f32 v5, v5, v6
	global_store_dword v2, v5, s[44:45] offset:64
	v_mul_f32_e32 v5, v34, v1
	v_mul_f32_e32 v6, v35, v4
	v_cndmask_b32_e32 v7, v5, v6, vcc
	s_nop 1
	v_mov_b32_dpp v7, v7 quad_perm:[1,0,3,2] row_mask:0xf bank_mask:0xf
	v_mul_f32_e32 v1, v18, v1
	v_mul_f32_e32 v4, v19, v4
	v_cndmask_b32_e32 v5, v7, v5, vcc
	v_cndmask_b32_e32 v6, v6, v7, vcc
	s_waitcnt vmcnt(31)
	v_lshlrev_b32_e32 v8, 16, v111
	v_and_b32_e32 v7, 0xffff0000, v111
	v_mul_f32_e32 v5, v5, v8
	v_mul_f32_e32 v6, v6, v7
	v_cvt_pk_bf16_f32 v5, v5, v6
	global_store_dword v2, v5, s[44:45] offset:128
	v_cndmask_b32_e32 v5, v1, v4, vcc
	s_nop 1
	v_mov_b32_dpp v5, v5 quad_perm:[1,0,3,2] row_mask:0xf bank_mask:0xf
	v_cndmask_b32_e32 v1, v5, v1, vcc
	v_cndmask_b32_e32 v4, v4, v5, vcc
	s_waitcnt vmcnt(31)
	v_lshlrev_b32_e32 v6, 16, v112
	v_and_b32_e32 v5, 0xffff0000, v112
	v_mul_f32_e32 v1, v1, v6
	v_mul_f32_e32 v4, v4, v5
	v_cvt_pk_bf16_f32 v1, v1, v4
	global_store_dword v2, v1, s[44:45] offset:192

.LBB0_1045:
	s_and_saveexec_b64 s[48:49], s[44:45]
	ds_write_b32 v180, v81
	s_or_b64 exec, exec, s[48:49]
	s_waitcnt lgkmcnt(0)
	v_lshl_add_u32 v68, v164, 4, s11
	ds_read_b128 v[70:73], v68
	v_and_b32_e32 v1, 1, v165
	v_cmp_eq_u32_e32 vcc, 0, v1
	v_and_b32_e32 v2, 30, v165
	v_lshlrev_b32_e32 v1, 10, v1
	s_waitcnt lgkmcnt(0)
	v_rcp_f32_e32 v69, v70
	v_rcp_f32_e32 v70, v71
	v_lshlrev_b32_e32 v71, 12, v164
	s_ashr_i32 s47, s46, 31
	v_or3_b32 v1, v71, v1, v2
	v_mul_f32_e32 v2, v52, v69
	v_mul_f32_e32 v52, v53, v70
	s_lshl_b64 s[16:17], s[46:47], 11
	v_readlane_b32 s13, v253, 53
	v_cndmask_b32_e32 v53, v2, v52, vcc
	s_add_u32 s13, s13, s16
	v_readlane_b32 s18, v253, 54
	s_nop 1
	v_mov_b32_dpp v53, v53 quad_perm:[1,0,3,2] row_mask:0xf bank_mask:0xf
	s_addc_u32 s18, s18, s17
	s_lshl_b32 s1, s1, 1
	s_add_u32 s13, s13, s1
	s_addc_u32 s18, s18, 0
	s_lshl_b32 s9, s9, 1
	s_add_u32 s46, s13, s9
	s_addc_u32 s47, s18, 0
	v_cndmask_b32_e32 v71, v53, v2, vcc
	v_lshlrev_b32_e32 v2, 1, v1
	v_or_b32_e32 v74, 0x1000, v2
	v_or_b32_e32 v75, 0x4000, v2
	v_or_b32_e32 v76, 0x5000, v2
	v_or_b32_e32 v77, 0x8000, v2
	v_or_b32_e32 v78, 0x9000, v2
	v_or_b32_e32 v79, 0xc000, v2
	v_or_b32_e32 v80, 0xd000, v2
	global_load_dword v81, v2, s[46:47]
	global_load_dword v82, v2, s[46:47] offset:64
	global_load_dword v83, v2, s[46:47] offset:128
	global_load_dword v84, v2, s[46:47] offset:192
	global_load_dword v85, v74, s[46:47]
	global_load_dword v86, v74, s[46:47] offset:64
	global_load_dword v87, v74, s[46:47] offset:128
	global_load_dword v88, v74, s[46:47] offset:192
	global_load_dword v89, v75, s[46:47]
	global_load_dword v90, v75, s[46:47] offset:64
	global_load_dword v91, v75, s[46:47] offset:128
	global_load_dword v92, v75, s[46:47] offset:192
	global_load_dword v93, v76, s[46:47]
	global_load_dword v94, v76, s[46:47] offset:64
	global_load_dword v95, v76, s[46:47] offset:128
	global_load_dword v96, v76, s[46:47] offset:192
	global_load_dword v97, v77, s[46:47]
	global_load_dword v98, v77, s[46:47] offset:64
	global_load_dword v99, v77, s[46:47] offset:128
	global_load_dword v100, v77, s[46:47] offset:192
	global_load_dword v101, v78, s[46:47]
	global_load_dword v102, v78, s[46:47] offset:64
	global_load_dword v103, v78, s[46:47] offset:128
	global_load_dword v104, v78, s[46:47] offset:192
	global_load_dword v105, v79, s[46:47]
	global_load_dword v106, v79, s[46:47] offset:64
	global_load_dword v107, v79, s[46:47] offset:128
	global_load_dword v108, v79, s[46:47] offset:192
	global_load_dword v109, v80, s[46:47]
	global_load_dword v110, v80, s[46:47] offset:64
	global_load_dword v111, v80, s[46:47] offset:128
	global_load_dword v112, v80, s[46:47] offset:192
	s_nop 0
	s_nop 0
	v_readlane_b32 s13, v253, 51
	s_add_u32 s13, s13, s16
	v_readlane_b32 s16, v253, 52
	s_addc_u32 s16, s16, s17
	s_add_u32 s1, s13, s1
	s_addc_u32 s13, s16, 0
	v_cndmask_b32_e32 v52, v52, v53, vcc
	s_add_u32 s44, s1, s9
	s_addc_u32 s45, s13, 0
	s_waitcnt vmcnt(31)
	v_lshlrev_b32_e32 v53, 16, v81
	v_and_b32_e32 v1, 0xffff0000, v81
	v_mul_f32_e32 v53, v71, v53
	v_mul_f32_e32 v1, v52, v1
	v_cvt_pk_bf16_f32 v1, v53, v1
	global_store_dword v2, v1, s[44:45]
	v_mul_f32_e32 v1, v36, v69
	v_mul_f32_e32 v36, v37, v70
	v_cndmask_b32_e32 v37, v1, v36, vcc
	s_nop 1
	v_mov_b32_dpp v37, v37 quad_perm:[1,0,3,2] row_mask:0xf bank_mask:0xf
	v_cndmask_b32_e32 v1, v37, v1, vcc
	v_cndmask_b32_e32 v36, v36, v37, vcc
	s_waitcnt vmcnt(31)
	v_lshlrev_b32_e32 v52, 16, v82
	v_and_b32_e32 v37, 0xffff0000, v82
	v_mul_f32_e32 v1, v1, v52
	v_mul_f32_e32 v36, v36, v37
	v_cvt_pk_bf16_f32 v1, v1, v36
	global_store_dword v2, v1, s[44:45] offset:64
	v_mul_f32_e32 v1, v20, v69
	v_mul_f32_e32 v20, v21, v70
	v_cndmask_b32_e32 v21, v1, v20, vcc
	s_nop 1
	v_mov_b32_dpp v21, v21 quad_perm:[1,0,3,2] row_mask:0xf bank_mask:0xf
	v_cndmask_b32_e32 v1, v21, v1, vcc
	v_cndmask_b32_e32 v20, v20, v21, vcc
	s_waitcnt vmcnt(31)
	v_lshlrev_b32_e32 v36, 16, v83
	v_and_b32_e32 v21, 0xffff0000, v83
	v_mul_f32_e32 v1, v1, v36
	v_mul_f32_e32 v20, v20, v21
	v_cvt_pk_bf16_f32 v1, v1, v20
	global_store_dword v2, v1, s[44:45] offset:128
	v_mul_f32_e32 v1, v4, v69
	v_mul_f32_e32 v4, v5, v70
	v_cndmask_b32_e32 v5, v1, v4, vcc
	s_nop 1
	v_mov_b32_dpp v5, v5 quad_perm:[1,0,3,2] row_mask:0xf bank_mask:0xf
	v_cndmask_b32_e32 v1, v5, v1, vcc
	v_cndmask_b32_e32 v4, v4, v5, vcc
	s_waitcnt vmcnt(31)
	v_lshlrev_b32_e32 v20, 16, v84
	v_and_b32_e32 v5, 0xffff0000, v84
	v_mul_f32_e32 v1, v1, v20
	v_mul_f32_e32 v4, v4, v5
	v_cvt_pk_bf16_f32 v1, v1, v4
	global_store_dword v2, v1, s[44:45] offset:192
	v_rcp_f32_e32 v1, v72
	v_rcp_f32_e32 v4, v73
	v_mul_f32_e32 v5, v54, v1
	v_mul_f32_e32 v20, v55, v4
	v_cndmask_b32_e32 v21, v5, v20, vcc
	s_nop 1
	v_mov_b32_dpp v21, v21 quad_perm:[1,0,3,2] row_mask:0xf bank_mask:0xf
	v_cndmask_b32_e32 v5, v21, v5, vcc
	v_cndmask_b32_e32 v20, v20, v21, vcc
	v_or_b32_e32 v21, 0x1000, v2
	s_waitcnt vmcnt(31)
	v_lshlrev_b32_e32 v37, 16, v85
	v_and_b32_e32 v36, 0xffff0000, v85
	v_mul_f32_e32 v5, v5, v37
	v_mul_f32_e32 v20, v20, v36
	v_cvt_pk_bf16_f32 v5, v5, v20
	global_store_dword v21, v5, s[44:45]
	v_mul_f32_e32 v5, v38, v1
	v_mul_f32_e32 v20, v39, v4
	v_cndmask_b32_e32 v36, v5, v20, vcc
	s_nop 1
	v_mov_b32_dpp v36, v36 quad_perm:[1,0,3,2] row_mask:0xf bank_mask:0xf
	v_cndmask_b32_e32 v5, v36, v5, vcc
	v_cndmask_b32_e32 v20, v20, v36, vcc
	s_waitcnt vmcnt(31)
	v_lshlrev_b32_e32 v37, 16, v86
	v_and_b32_e32 v36, 0xffff0000, v86
	v_mul_f32_e32 v5, v5, v37
	v_mul_f32_e32 v20, v20, v36
	v_cvt_pk_bf16_f32 v5, v5, v20
	global_store_dword v21, v5, s[44:45] offset:64
	v_mul_f32_e32 v5, v22, v1
	v_mul_f32_e32 v20, v23, v4
	v_cndmask_b32_e32 v22, v5, v20, vcc
	s_nop 1
	v_mov_b32_dpp v22, v22 quad_perm:[1,0,3,2] row_mask:0xf bank_mask:0xf
	v_mul_f32_e32 v1, v6, v1
	v_mul_f32_e32 v4, v7, v4
	v_cndmask_b32_e32 v5, v22, v5, vcc
	v_cndmask_b32_e32 v20, v20, v22, vcc
	s_waitcnt vmcnt(31)
	v_lshlrev_b32_e32 v23, 16, v87
	v_and_b32_e32 v22, 0xffff0000, v87
	v_mul_f32_e32 v5, v5, v23
	v_mul_f32_e32 v20, v20, v22
	v_cvt_pk_bf16_f32 v5, v5, v20
	global_store_dword v21, v5, s[44:45] offset:128
	v_cndmask_b32_e32 v5, v1, v4, vcc
	s_nop 1
	v_mov_b32_dpp v5, v5 quad_perm:[1,0,3,2] row_mask:0xf bank_mask:0xf
	v_cndmask_b32_e32 v1, v5, v1, vcc
	v_cndmask_b32_e32 v4, v4, v5, vcc
	s_waitcnt vmcnt(31)
	v_lshlrev_b32_e32 v6, 16, v88
	v_and_b32_e32 v5, 0xffff0000, v88
	v_mul_f32_e32 v1, v1, v6
	v_mul_f32_e32 v4, v4, v5
	v_cvt_pk_bf16_f32 v1, v1, v4
	ds_read_b128 v[4:7], v68 offset:32
	global_store_dword v21, v1, s[44:45] offset:192
	s_waitcnt lgkmcnt(0)
	v_rcp_f32_e32 v4, v4
	v_rcp_f32_e32 v5, v5
	v_mul_f32_e32 v1, v56, v4
	v_mul_f32_e32 v20, v57, v5
	v_cndmask_b32_e32 v21, v1, v20, vcc
	s_nop 1
	v_mov_b32_dpp v21, v21 quad_perm:[1,0,3,2] row_mask:0xf bank_mask:0xf
	v_cndmask_b32_e32 v1, v21, v1, vcc
	v_cndmask_b32_e32 v20, v20, v21, vcc
	v_or_b32_e32 v21, 0x4000, v2
	s_waitcnt vmcnt(31)
	v_lshlrev_b32_e32 v23, 16, v89
	v_and_b32_e32 v22, 0xffff0000, v89
	v_mul_f32_e32 v1, v1, v23
	v_mul_f32_e32 v20, v20, v22
	v_cvt_pk_bf16_f32 v1, v1, v20
	global_store_dword v21, v1, s[44:45]
	v_mul_f32_e32 v1, v40, v4
	v_mul_f32_e32 v20, v41, v5
	v_cndmask_b32_e32 v22, v1, v20, vcc
	s_nop 1
	v_mov_b32_dpp v22, v22 quad_perm:[1,0,3,2] row_mask:0xf bank_mask:0xf
	v_cndmask_b32_e32 v1, v22, v1, vcc
	v_cndmask_b32_e32 v20, v20, v22, vcc
	s_waitcnt vmcnt(31)
	v_lshlrev_b32_e32 v23, 16, v90
	v_and_b32_e32 v22, 0xffff0000, v90
	v_mul_f32_e32 v1, v1, v23
	v_mul_f32_e32 v20, v20, v22
	v_cvt_pk_bf16_f32 v1, v1, v20
	global_store_dword v21, v1, s[44:45] offset:64
	v_mul_f32_e32 v1, v24, v4
	v_mul_f32_e32 v20, v25, v5
	v_cndmask_b32_e32 v22, v1, v20, vcc
	s_nop 1
	v_mov_b32_dpp v22, v22 quad_perm:[1,0,3,2] row_mask:0xf bank_mask:0xf
	v_cndmask_b32_e32 v1, v22, v1, vcc
	v_cndmask_b32_e32 v20, v20, v22, vcc
	s_waitcnt vmcnt(31)
	v_lshlrev_b32_e32 v23, 16, v91
	v_and_b32_e32 v22, 0xffff0000, v91
	v_mul_f32_e32 v1, v1, v23
	v_mul_f32_e32 v20, v20, v22
	v_cvt_pk_bf16_f32 v1, v1, v20
	global_store_dword v21, v1, s[44:45] offset:128
	v_mul_f32_e32 v1, v8, v4
	v_mul_f32_e32 v4, v9, v5
	v_cndmask_b32_e32 v5, v1, v4, vcc
	s_nop 1
	v_mov_b32_dpp v5, v5 quad_perm:[1,0,3,2] row_mask:0xf bank_mask:0xf
	v_cndmask_b32_e32 v1, v5, v1, vcc
	v_cndmask_b32_e32 v4, v4, v5, vcc
	s_waitcnt vmcnt(31)
	v_lshlrev_b32_e32 v8, 16, v92
	v_and_b32_e32 v5, 0xffff0000, v92
	v_mul_f32_e32 v1, v1, v8
	v_mul_f32_e32 v4, v4, v5
	v_cvt_pk_bf16_f32 v1, v1, v4
	global_store_dword v21, v1, s[44:45] offset:192
	v_rcp_f32_e32 v1, v6
	v_rcp_f32_e32 v4, v7
	v_mul_f32_e32 v5, v58, v1
	v_mul_f32_e32 v6, v59, v4
	v_cndmask_b32_e32 v7, v5, v6, vcc
	s_nop 1
	v_mov_b32_dpp v7, v7 quad_perm:[1,0,3,2] row_mask:0xf bank_mask:0xf
	v_cndmask_b32_e32 v5, v7, v5, vcc
	v_cndmask_b32_e32 v6, v6, v7, vcc
	v_or_b32_e32 v7, 0x5000, v2
	s_waitcnt vmcnt(31)
	v_lshlrev_b32_e32 v9, 16, v93
	v_and_b32_e32 v8, 0xffff0000, v93
	v_mul_f32_e32 v5, v5, v9
	v_mul_f32_e32 v6, v6, v8
	v_cvt_pk_bf16_f32 v5, v5, v6
	global_store_dword v7, v5, s[44:45]
	v_mul_f32_e32 v5, v42, v1
	v_mul_f32_e32 v6, v43, v4
	v_cndmask_b32_e32 v8, v5, v6, vcc
	s_nop 1
	v_mov_b32_dpp v8, v8 quad_perm:[1,0,3,2] row_mask:0xf bank_mask:0xf
	v_cndmask_b32_e32 v5, v8, v5, vcc
	v_cndmask_b32_e32 v6, v6, v8, vcc
	s_waitcnt vmcnt(31)
	v_lshlrev_b32_e32 v9, 16, v94
	v_and_b32_e32 v8, 0xffff0000, v94
	v_mul_f32_e32 v5, v5, v9
	v_mul_f32_e32 v6, v6, v8
	v_cvt_pk_bf16_f32 v5, v5, v6
	global_store_dword v7, v5, s[44:45] offset:64
	v_mul_f32_e32 v5, v26, v1
	v_mul_f32_e32 v6, v27, v4
	v_cndmask_b32_e32 v8, v5, v6, vcc
	s_nop 1
	v_mov_b32_dpp v8, v8 quad_perm:[1,0,3,2] row_mask:0xf bank_mask:0xf
	v_mul_f32_e32 v1, v10, v1
	v_mul_f32_e32 v4, v11, v4
	v_cndmask_b32_e32 v5, v8, v5, vcc
	v_cndmask_b32_e32 v6, v6, v8, vcc
	s_waitcnt vmcnt(31)
	v_lshlrev_b32_e32 v9, 16, v95
	v_and_b32_e32 v8, 0xffff0000, v95
	v_mul_f32_e32 v5, v5, v9
	v_mul_f32_e32 v6, v6, v8
	v_cvt_pk_bf16_f32 v5, v5, v6
	global_store_dword v7, v5, s[44:45] offset:128
	v_cndmask_b32_e32 v5, v1, v4, vcc
	s_nop 1
	v_mov_b32_dpp v5, v5 quad_perm:[1,0,3,2] row_mask:0xf bank_mask:0xf
	v_cndmask_b32_e32 v1, v5, v1, vcc
	v_cndmask_b32_e32 v4, v4, v5, vcc
	s_waitcnt vmcnt(31)
	v_lshlrev_b32_e32 v6, 16, v96
	v_and_b32_e32 v5, 0xffff0000, v96
	v_mul_f32_e32 v1, v1, v6
	v_mul_f32_e32 v4, v4, v5
	v_cvt_pk_bf16_f32 v1, v1, v4
	global_store_dword v7, v1, s[44:45] offset:192
	ds_read_b128 v[4:7], v68 offset:64
	s_waitcnt lgkmcnt(0)
	v_rcp_f32_e32 v1, v4
	v_rcp_f32_e32 v4, v5
	v_mul_f32_e32 v5, v60, v1
	v_mul_f32_e32 v8, v61, v4
	v_cndmask_b32_e32 v9, v5, v8, vcc
	s_nop 1
	v_mov_b32_dpp v9, v9 quad_perm:[1,0,3,2] row_mask:0xf bank_mask:0xf
	v_cndmask_b32_e32 v5, v9, v5, vcc
	v_cndmask_b32_e32 v8, v8, v9, vcc
	v_or_b32_e32 v9, 0x8000, v2
	s_waitcnt vmcnt(31)
	v_lshlrev_b32_e32 v11, 16, v97
	v_and_b32_e32 v10, 0xffff0000, v97
	v_mul_f32_e32 v5, v5, v11
	v_mul_f32_e32 v8, v8, v10
	v_cvt_pk_bf16_f32 v5, v5, v8
	global_store_dword v9, v5, s[44:45]
	v_mul_f32_e32 v5, v44, v1
	v_mul_f32_e32 v8, v45, v4
	v_cndmask_b32_e32 v10, v5, v8, vcc
	s_nop 1
	v_mov_b32_dpp v10, v10 quad_perm:[1,0,3,2] row_mask:0xf bank_mask:0xf
	v_cndmask_b32_e32 v5, v10, v5, vcc
	v_cndmask_b32_e32 v8, v8, v10, vcc
	s_waitcnt vmcnt(31)
	v_lshlrev_b32_e32 v11, 16, v98
	v_and_b32_e32 v10, 0xffff0000, v98
	v_mul_f32_e32 v5, v5, v11
	v_mul_f32_e32 v8, v8, v10
	v_cvt_pk_bf16_f32 v5, v5, v8
	global_store_dword v9, v5, s[44:45] offset:64
	v_mul_f32_e32 v5, v28, v1
	v_mul_f32_e32 v8, v29, v4
	v_cndmask_b32_e32 v10, v5, v8, vcc
	s_nop 1
	v_mov_b32_dpp v10, v10 quad_perm:[1,0,3,2] row_mask:0xf bank_mask:0xf
	v_mul_f32_e32 v1, v12, v1
	v_mul_f32_e32 v4, v13, v4
	v_cndmask_b32_e32 v5, v10, v5, vcc
	v_cndmask_b32_e32 v8, v8, v10, vcc
	s_waitcnt vmcnt(31)
	v_lshlrev_b32_e32 v11, 16, v99
	v_and_b32_e32 v10, 0xffff0000, v99
	v_mul_f32_e32 v5, v5, v11
	v_mul_f32_e32 v8, v8, v10
	v_cvt_pk_bf16_f32 v5, v5, v8
	global_store_dword v9, v5, s[44:45] offset:128
	v_cndmask_b32_e32 v5, v1, v4, vcc
	s_nop 1
	v_mov_b32_dpp v5, v5 quad_perm:[1,0,3,2] row_mask:0xf bank_mask:0xf
	v_cndmask_b32_e32 v1, v5, v1, vcc
	v_cndmask_b32_e32 v4, v4, v5, vcc
	s_waitcnt vmcnt(31)
	v_lshlrev_b32_e32 v8, 16, v100
	v_and_b32_e32 v5, 0xffff0000, v100
	v_mul_f32_e32 v1, v1, v8
	v_mul_f32_e32 v4, v4, v5
	v_cvt_pk_bf16_f32 v1, v1, v4
	global_store_dword v9, v1, s[44:45] offset:192
	v_rcp_f32_e32 v1, v6
	v_rcp_f32_e32 v4, v7
	v_mul_f32_e32 v5, v62, v1
	v_mul_f32_e32 v6, v63, v4
	v_cndmask_b32_e32 v7, v5, v6, vcc
	s_nop 1
	v_mov_b32_dpp v7, v7 quad_perm:[1,0,3,2] row_mask:0xf bank_mask:0xf
	v_cndmask_b32_e32 v5, v7, v5, vcc
	v_cndmask_b32_e32 v6, v6, v7, vcc
	v_or_b32_e32 v7, 0x9000, v2
	s_waitcnt vmcnt(31)
	v_lshlrev_b32_e32 v9, 16, v101
	v_and_b32_e32 v8, 0xffff0000, v101
	v_mul_f32_e32 v5, v5, v9
	v_mul_f32_e32 v6, v6, v8
	v_cvt_pk_bf16_f32 v5, v5, v6
	global_store_dword v7, v5, s[44:45]
	v_mul_f32_e32 v5, v46, v1
	v_mul_f32_e32 v6, v47, v4
	v_cndmask_b32_e32 v8, v5, v6, vcc
	s_nop 1
	v_mov_b32_dpp v8, v8 quad_perm:[1,0,3,2] row_mask:0xf bank_mask:0xf
	v_cndmask_b32_e32 v5, v8, v5, vcc
	v_cndmask_b32_e32 v6, v6, v8, vcc
	s_waitcnt vmcnt(31)
	v_lshlrev_b32_e32 v9, 16, v102
	v_and_b32_e32 v8, 0xffff0000, v102
	v_mul_f32_e32 v5, v5, v9
	v_mul_f32_e32 v6, v6, v8
	v_cvt_pk_bf16_f32 v5, v5, v6
	global_store_dword v7, v5, s[44:45] offset:64
	v_mul_f32_e32 v5, v30, v1
	v_mul_f32_e32 v6, v31, v4
	v_cndmask_b32_e32 v8, v5, v6, vcc
	s_nop 1
	v_mov_b32_dpp v8, v8 quad_perm:[1,0,3,2] row_mask:0xf bank_mask:0xf
	v_mul_f32_e32 v1, v14, v1
	v_mul_f32_e32 v4, v15, v4
	v_cndmask_b32_e32 v5, v8, v5, vcc
	v_cndmask_b32_e32 v6, v6, v8, vcc
	s_waitcnt vmcnt(31)
	v_lshlrev_b32_e32 v9, 16, v103
	v_and_b32_e32 v8, 0xffff0000, v103
	v_mul_f32_e32 v5, v5, v9
	v_mul_f32_e32 v6, v6, v8
	v_cvt_pk_bf16_f32 v5, v5, v6
	global_store_dword v7, v5, s[44:45] offset:128
	v_cndmask_b32_e32 v5, v1, v4, vcc
	s_nop 1
	v_mov_b32_dpp v5, v5 quad_perm:[1,0,3,2] row_mask:0xf bank_mask:0xf
	v_cndmask_b32_e32 v1, v5, v1, vcc
	v_cndmask_b32_e32 v4, v4, v5, vcc
	s_waitcnt vmcnt(31)
	v_lshlrev_b32_e32 v6, 16, v104
	v_and_b32_e32 v5, 0xffff0000, v104
	v_mul_f32_e32 v1, v1, v6
	v_mul_f32_e32 v4, v4, v5
	v_cvt_pk_bf16_f32 v1, v1, v4
	global_store_dword v7, v1, s[44:45] offset:192
	ds_read_b128 v[4:7], v68 offset:96
	s_waitcnt lgkmcnt(0)
	v_rcp_f32_e32 v4, v4
	v_rcp_f32_e32 v5, v5
	v_mul_f32_e32 v1, v64, v4
	v_mul_f32_e32 v8, v65, v5
	v_cndmask_b32_e32 v9, v1, v8, vcc
	s_nop 1
	v_mov_b32_dpp v9, v9 quad_perm:[1,0,3,2] row_mask:0xf bank_mask:0xf
	v_cndmask_b32_e32 v1, v9, v1, vcc
	v_cndmask_b32_e32 v8, v8, v9, vcc
	v_or_b32_e32 v9, 0xc000, v2
	v_or_b32_e32 v2, 0xd000, v2
	s_waitcnt vmcnt(31)
	v_lshlrev_b32_e32 v11, 16, v105
	v_and_b32_e32 v10, 0xffff0000, v105
	v_mul_f32_e32 v1, v1, v11
	v_mul_f32_e32 v8, v8, v10
	v_cvt_pk_bf16_f32 v1, v1, v8
	global_store_dword v9, v1, s[44:45]
	v_mul_f32_e32 v1, v48, v4
	v_mul_f32_e32 v8, v49, v5
	v_cndmask_b32_e32 v10, v1, v8, vcc
	s_nop 1
	v_mov_b32_dpp v10, v10 quad_perm:[1,0,3,2] row_mask:0xf bank_mask:0xf
	v_cndmask_b32_e32 v1, v10, v1, vcc
	v_cndmask_b32_e32 v8, v8, v10, vcc
	s_waitcnt vmcnt(31)
	v_lshlrev_b32_e32 v11, 16, v106
	v_and_b32_e32 v10, 0xffff0000, v106
	v_mul_f32_e32 v1, v1, v11
	v_mul_f32_e32 v8, v8, v10
	v_cvt_pk_bf16_f32 v1, v1, v8
	global_store_dword v9, v1, s[44:45] offset:64
	v_mul_f32_e32 v1, v32, v4
	v_mul_f32_e32 v8, v33, v5
	v_cndmask_b32_e32 v10, v1, v8, vcc
	s_nop 1
	v_mov_b32_dpp v10, v10 quad_perm:[1,0,3,2] row_mask:0xf bank_mask:0xf
	v_cndmask_b32_e32 v1, v10, v1, vcc
	v_cndmask_b32_e32 v8, v8, v10, vcc
	s_waitcnt vmcnt(31)
	v_lshlrev_b32_e32 v11, 16, v107
	v_and_b32_e32 v10, 0xffff0000, v107
	v_mul_f32_e32 v1, v1, v11
	v_mul_f32_e32 v8, v8, v10
	v_cvt_pk_bf16_f32 v1, v1, v8
	global_store_dword v9, v1, s[44:45] offset:128
	v_mul_f32_e32 v1, v16, v4
	v_mul_f32_e32 v4, v17, v5
	v_cndmask_b32_e32 v5, v1, v4, vcc
	s_nop 1
	v_mov_b32_dpp v5, v5 quad_perm:[1,0,3,2] row_mask:0xf bank_mask:0xf
	v_cndmask_b32_e32 v1, v5, v1, vcc
	v_cndmask_b32_e32 v4, v4, v5, vcc
	s_waitcnt vmcnt(31)
	v_lshlrev_b32_e32 v8, 16, v108
	v_and_b32_e32 v5, 0xffff0000, v108
	v_mul_f32_e32 v1, v1, v8
	v_mul_f32_e32 v4, v4, v5
	v_cvt_pk_bf16_f32 v1, v1, v4
	global_store_dword v9, v1, s[44:45] offset:192
	v_rcp_f32_e32 v1, v6
	v_rcp_f32_e32 v4, v7
	v_mul_f32_e32 v5, v66, v1
	v_mul_f32_e32 v6, v67, v4
	v_cndmask_b32_e32 v7, v5, v6, vcc
	s_nop 1
	v_mov_b32_dpp v7, v7 quad_perm:[1,0,3,2] row_mask:0xf bank_mask:0xf
	v_cndmask_b32_e32 v5, v7, v5, vcc
	v_cndmask_b32_e32 v6, v6, v7, vcc
	s_waitcnt vmcnt(31)
	v_lshlrev_b32_e32 v8, 16, v109
	v_and_b32_e32 v7, 0xffff0000, v109
	v_mul_f32_e32 v5, v5, v8
	v_mul_f32_e32 v6, v6, v7
	v_cvt_pk_bf16_f32 v5, v5, v6
	global_store_dword v2, v5, s[44:45]
	v_mul_f32_e32 v5, v50, v1
	v_mul_f32_e32 v6, v51, v4
	v_cndmask_b32_e32 v7, v5, v6, vcc
	s_nop 1
	v_mov_b32_dpp v7, v7 quad_perm:[1,0,3,2] row_mask:0xf bank_mask:0xf
	v_cndmask_b32_e32 v5, v7, v5, vcc
	v_cndmask_b32_e32 v6, v6, v7, vcc
	s_waitcnt vmcnt(31)
	v_lshlrev_b32_e32 v8, 16, v110
	v_and_b32_e32 v7, 0xffff0000, v110
	v_mul_f32_e32 v5, v5, v8
	v_mul_f32_e32 v6, v6, v7
	v_cvt_pk_bf16_f32 v5, v5, v6
	global_store_dword v2, v5, s[44:45] offset:64
	v_mul_f32_e32 v5, v34, v1
	v_mul_f32_e32 v6, v35, v4
	v_cndmask_b32_e32 v7, v5, v6, vcc
	s_nop 1
	v_mov_b32_dpp v7, v7 quad_perm:[1,0,3,2] row_mask:0xf bank_mask:0xf
	v_mul_f32_e32 v1, v18, v1
	v_mul_f32_e32 v4, v19, v4
	v_cndmask_b32_e32 v5, v7, v5, vcc
	v_cndmask_b32_e32 v6, v6, v7, vcc
	s_waitcnt vmcnt(31)
	v_lshlrev_b32_e32 v8, 16, v111
	v_and_b32_e32 v7, 0xffff0000, v111
	v_mul_f32_e32 v5, v5, v8
	v_mul_f32_e32 v6, v6, v7
	v_cvt_pk_bf16_f32 v5, v5, v6
	global_store_dword v2, v5, s[44:45] offset:128
	v_cndmask_b32_e32 v5, v1, v4, vcc
	s_nop 1
	v_mov_b32_dpp v5, v5 quad_perm:[1,0,3,2] row_mask:0xf bank_mask:0xf
	v_cndmask_b32_e32 v1, v5, v1, vcc
	v_cndmask_b32_e32 v4, v4, v5, vcc
	s_waitcnt vmcnt(31)
	v_lshlrev_b32_e32 v6, 16, v112
	v_and_b32_e32 v5, 0xffff0000, v112
	v_mul_f32_e32 v1, v1, v6
	v_mul_f32_e32 v4, v4, v5
	v_cvt_pk_bf16_f32 v1, v1, v4
	global_store_dword v2, v1, s[44:45] offset:192

.LBB0_1071:
	s_or_b64 exec, exec, s[44:45]
	s_ashr_i32 s47, s46, 31
	s_lshl_b64 s[18:19], s[46:47], 12
	v_readlane_b32 s1, v254, 29
	s_add_u32 s1, s1, s18
	v_readlane_b32 s9, v254, 30
	s_addc_u32 s9, s9, s19
	s_lshl_b32 s13, s16, 8
	s_add_u32 s46, s1, s13
	s_addc_u32 s47, s9, 0
	v_readlane_b32 s1, v254, 31
	s_add_u32 s1, s1, s18
	v_readlane_b32 s9, v254, 32
	s_addc_u32 s9, s9, s19
	s_add_u32 s44, s1, s13
	v_readlane_b32 s1, v254, 28
	s_waitcnt lgkmcnt(0)
	v_and_b32_e32 v1, 1, v164
	v_cmp_eq_u32_e32 vcc, 0, v1
	v_lshl_add_u32 v8, v172, 4, s1
	ds_read_b128 v[4:7], v8
	v_and_b32_e32 v2, 30, v164
	v_lshlrev_b32_e32 v9, 13, v172
	v_lshlrev_b32_e32 v1, 11, v1
	v_or3_b32 v1, v9, v1, v2
	s_waitcnt lgkmcnt(0)
	v_rcp_f32_e32 v4, v4
	v_rcp_f32_e32 v5, v5
	s_addc_u32 s45, s9, 0
	v_mul_f32_e32 v2, v66, v4
	v_mul_f32_e32 v9, v67, v5
	v_cndmask_b32_e32 v10, v2, v9, vcc
	s_nop 1
	v_mov_b32_dpp v10, v10 quad_perm:[1,0,3,2] row_mask:0xf bank_mask:0xf
	v_cndmask_b32_e32 v11, v10, v2, vcc
	v_lshlrev_b32_e32 v2, 1, v1
	v_or_b32_e32 v13, 0x2000, v2
	v_or_b32_e32 v14, 0x8000, v2
	v_or_b32_e32 v15, 0xa000, v2
	v_or_b32_e32 v16, 0x10000, v2
	v_or_b32_e32 v17, 0x12000, v2
	v_or_b32_e32 v66, 0x18000, v2
	v_or_b32_e32 v82, 0x1a000, v2
	global_load_dword v83, v2, s[46:47]
	global_load_dword v84, v2, s[46:47] offset:64
	global_load_dword v85, v2, s[46:47] offset:128
	global_load_dword v86, v2, s[46:47] offset:192
	global_load_dword v87, v13, s[46:47]
	global_load_dword v88, v13, s[46:47] offset:64
	global_load_dword v89, v13, s[46:47] offset:128
	global_load_dword v90, v13, s[46:47] offset:192
	global_load_dword v91, v14, s[46:47]
	global_load_dword v92, v14, s[46:47] offset:64
	global_load_dword v93, v14, s[46:47] offset:128
	global_load_dword v94, v14, s[46:47] offset:192
	global_load_dword v95, v15, s[46:47]
	global_load_dword v96, v15, s[46:47] offset:64
	global_load_dword v97, v15, s[46:47] offset:128
	global_load_dword v98, v15, s[46:47] offset:192
	global_load_dword v99, v16, s[46:47]
	global_load_dword v100, v16, s[46:47] offset:64
	global_load_dword v101, v16, s[46:47] offset:128
	global_load_dword v102, v16, s[46:47] offset:192
	global_load_dword v103, v17, s[46:47]
	global_load_dword v104, v17, s[46:47] offset:64
	global_load_dword v105, v17, s[46:47] offset:128
	global_load_dword v106, v17, s[46:47] offset:192
	global_load_dword v107, v66, s[46:47]
	global_load_dword v108, v66, s[46:47] offset:64
	global_load_dword v109, v66, s[46:47] offset:128
	global_load_dword v110, v66, s[46:47] offset:192
	global_load_dword v111, v82, s[46:47]
	global_load_dword v112, v82, s[46:47] offset:64
	global_load_dword v113, v82, s[46:47] offset:128
	global_load_dword v114, v82, s[46:47] offset:192
	s_nop 0
	s_nop 0
	v_cndmask_b32_e32 v9, v9, v10, vcc
	s_waitcnt vmcnt(31)
	v_lshlrev_b32_e32 v10, 16, v83
	v_and_b32_e32 v1, 0xffff0000, v83
	v_mul_f32_e32 v10, v11, v10
	v_mul_f32_e32 v1, v9, v1
	v_cvt_pk_bf16_f32 v1, v10, v1
	global_store_dword v2, v1, s[44:45]
	v_mul_f32_e32 v1, v50, v4
	v_mul_f32_e32 v9, v51, v5
	v_cndmask_b32_e32 v10, v1, v9, vcc
	s_nop 1
	v_mov_b32_dpp v10, v10 quad_perm:[1,0,3,2] row_mask:0xf bank_mask:0xf
	v_cndmask_b32_e32 v1, v10, v1, vcc
	v_cndmask_b32_e32 v9, v9, v10, vcc
	s_waitcnt vmcnt(31)
	v_lshlrev_b32_e32 v11, 16, v84
	v_and_b32_e32 v10, 0xffff0000, v84
	v_mul_f32_e32 v1, v1, v11
	v_mul_f32_e32 v9, v9, v10
	v_cvt_pk_bf16_f32 v1, v1, v9
	global_store_dword v2, v1, s[44:45] offset:64
	v_mul_f32_e32 v1, v34, v4
	v_mul_f32_e32 v9, v35, v5
	v_cndmask_b32_e32 v10, v1, v9, vcc
	s_nop 1
	v_mov_b32_dpp v10, v10 quad_perm:[1,0,3,2] row_mask:0xf bank_mask:0xf
	v_cndmask_b32_e32 v1, v10, v1, vcc
	v_cndmask_b32_e32 v9, v9, v10, vcc
	s_waitcnt vmcnt(31)
	v_lshlrev_b32_e32 v11, 16, v85
	v_and_b32_e32 v10, 0xffff0000, v85
	v_mul_f32_e32 v1, v1, v11
	v_mul_f32_e32 v9, v9, v10
	v_cvt_pk_bf16_f32 v1, v1, v9
	global_store_dword v2, v1, s[44:45] offset:128
	v_mul_f32_e32 v1, v18, v4
	v_mul_f32_e32 v4, v19, v5
	v_cndmask_b32_e32 v5, v1, v4, vcc
	s_nop 1
	v_mov_b32_dpp v5, v5 quad_perm:[1,0,3,2] row_mask:0xf bank_mask:0xf
	v_cndmask_b32_e32 v1, v5, v1, vcc
	v_cndmask_b32_e32 v4, v4, v5, vcc
	s_waitcnt vmcnt(31)
	v_lshlrev_b32_e32 v9, 16, v86
	v_and_b32_e32 v5, 0xffff0000, v86
	v_mul_f32_e32 v1, v1, v9
	v_mul_f32_e32 v4, v4, v5
	v_cvt_pk_bf16_f32 v1, v1, v4
	global_store_dword v2, v1, s[44:45] offset:192
	v_rcp_f32_e32 v1, v6
	v_rcp_f32_e32 v4, v7
	v_mul_f32_e32 v5, v68, v1
	v_mul_f32_e32 v6, v69, v4
	v_cndmask_b32_e32 v7, v5, v6, vcc
	s_nop 1
	v_mov_b32_dpp v7, v7 quad_perm:[1,0,3,2] row_mask:0xf bank_mask:0xf
	v_cndmask_b32_e32 v5, v7, v5, vcc
	v_cndmask_b32_e32 v6, v6, v7, vcc
	v_or_b32_e32 v7, 0x2000, v2
	s_waitcnt vmcnt(31)
	v_lshlrev_b32_e32 v10, 16, v87
	v_and_b32_e32 v9, 0xffff0000, v87
	v_mul_f32_e32 v5, v5, v10
	v_mul_f32_e32 v6, v6, v9
	v_cvt_pk_bf16_f32 v5, v5, v6
	global_store_dword v7, v5, s[44:45]
	v_mul_f32_e32 v5, v52, v1
	v_mul_f32_e32 v6, v53, v4
	v_cndmask_b32_e32 v9, v5, v6, vcc
	s_nop 1
	v_mov_b32_dpp v9, v9 quad_perm:[1,0,3,2] row_mask:0xf bank_mask:0xf
	v_cndmask_b32_e32 v5, v9, v5, vcc
	v_cndmask_b32_e32 v6, v6, v9, vcc
	s_waitcnt vmcnt(31)
	v_lshlrev_b32_e32 v10, 16, v88
	v_and_b32_e32 v9, 0xffff0000, v88
	v_mul_f32_e32 v5, v5, v10
	v_mul_f32_e32 v6, v6, v9
	v_cvt_pk_bf16_f32 v5, v5, v6
	global_store_dword v7, v5, s[44:45] offset:64
	v_mul_f32_e32 v5, v36, v1
	v_mul_f32_e32 v6, v37, v4
	v_cndmask_b32_e32 v9, v5, v6, vcc
	s_nop 1
	v_mov_b32_dpp v9, v9 quad_perm:[1,0,3,2] row_mask:0xf bank_mask:0xf
	v_mul_f32_e32 v1, v20, v1
	v_mul_f32_e32 v4, v21, v4
	v_cndmask_b32_e32 v5, v9, v5, vcc
	v_cndmask_b32_e32 v6, v6, v9, vcc
	s_waitcnt vmcnt(31)
	v_lshlrev_b32_e32 v10, 16, v89
	v_and_b32_e32 v9, 0xffff0000, v89
	v_mul_f32_e32 v5, v5, v10
	v_mul_f32_e32 v6, v6, v9
	v_cvt_pk_bf16_f32 v5, v5, v6
	global_store_dword v7, v5, s[44:45] offset:128
	v_cndmask_b32_e32 v5, v1, v4, vcc
	s_nop 1
	v_mov_b32_dpp v5, v5 quad_perm:[1,0,3,2] row_mask:0xf bank_mask:0xf
	v_cndmask_b32_e32 v1, v5, v1, vcc
	v_cndmask_b32_e32 v4, v4, v5, vcc
	s_waitcnt vmcnt(31)
	v_lshlrev_b32_e32 v6, 16, v90
	v_and_b32_e32 v5, 0xffff0000, v90
	v_mul_f32_e32 v1, v1, v6
	v_mul_f32_e32 v4, v4, v5
	v_cvt_pk_bf16_f32 v1, v1, v4
	global_store_dword v7, v1, s[44:45] offset:192
	ds_read_b128 v[4:7], v8 offset:32
	s_waitcnt lgkmcnt(0)
	v_rcp_f32_e32 v4, v4
	v_rcp_f32_e32 v5, v5
	v_mul_f32_e32 v1, v70, v4
	v_mul_f32_e32 v9, v71, v5
	v_cndmask_b32_e32 v10, v1, v9, vcc
	s_nop 1
	v_mov_b32_dpp v10, v10 quad_perm:[1,0,3,2] row_mask:0xf bank_mask:0xf
	v_cndmask_b32_e32 v1, v10, v1, vcc
	v_cndmask_b32_e32 v9, v9, v10, vcc
	v_or_b32_e32 v10, 0x8000, v2
	s_waitcnt vmcnt(31)
	v_lshlrev_b32_e32 v12, 16, v91
	v_and_b32_e32 v11, 0xffff0000, v91
	v_mul_f32_e32 v1, v1, v12
	v_mul_f32_e32 v9, v9, v11
	v_cvt_pk_bf16_f32 v1, v1, v9
	global_store_dword v10, v1, s[44:45]
	v_mul_f32_e32 v1, v54, v4
	v_mul_f32_e32 v9, v55, v5
	v_cndmask_b32_e32 v11, v1, v9, vcc
	s_nop 1
	v_mov_b32_dpp v11, v11 quad_perm:[1,0,3,2] row_mask:0xf bank_mask:0xf
	v_cndmask_b32_e32 v1, v11, v1, vcc
	v_cndmask_b32_e32 v9, v9, v11, vcc
	s_waitcnt vmcnt(31)
	v_lshlrev_b32_e32 v12, 16, v92
	v_and_b32_e32 v11, 0xffff0000, v92
	v_mul_f32_e32 v1, v1, v12
	v_mul_f32_e32 v9, v9, v11
	v_cvt_pk_bf16_f32 v1, v1, v9
	global_store_dword v10, v1, s[44:45] offset:64
	v_mul_f32_e32 v1, v38, v4
	v_mul_f32_e32 v9, v39, v5
	v_cndmask_b32_e32 v11, v1, v9, vcc
	s_nop 1
	v_mov_b32_dpp v11, v11 quad_perm:[1,0,3,2] row_mask:0xf bank_mask:0xf
	v_cndmask_b32_e32 v1, v11, v1, vcc
	v_cndmask_b32_e32 v9, v9, v11, vcc
	s_waitcnt vmcnt(31)
	v_lshlrev_b32_e32 v12, 16, v93
	v_and_b32_e32 v11, 0xffff0000, v93
	v_mul_f32_e32 v1, v1, v12
	v_mul_f32_e32 v9, v9, v11
	v_cvt_pk_bf16_f32 v1, v1, v9
	global_store_dword v10, v1, s[44:45] offset:128
	v_mul_f32_e32 v1, v22, v4
	v_mul_f32_e32 v4, v23, v5
	v_cndmask_b32_e32 v5, v1, v4, vcc
	s_nop 1
	v_mov_b32_dpp v5, v5 quad_perm:[1,0,3,2] row_mask:0xf bank_mask:0xf
	v_cndmask_b32_e32 v1, v5, v1, vcc
	v_cndmask_b32_e32 v4, v4, v5, vcc
	s_waitcnt vmcnt(31)
	v_lshlrev_b32_e32 v9, 16, v94
	v_and_b32_e32 v5, 0xffff0000, v94
	v_mul_f32_e32 v1, v1, v9
	v_mul_f32_e32 v4, v4, v5
	v_cvt_pk_bf16_f32 v1, v1, v4
	global_store_dword v10, v1, s[44:45] offset:192
	v_rcp_f32_e32 v1, v6
	v_rcp_f32_e32 v4, v7
	v_mul_f32_e32 v5, v72, v1
	v_mul_f32_e32 v6, v73, v4
	v_cndmask_b32_e32 v7, v5, v6, vcc
	s_nop 1
	v_mov_b32_dpp v7, v7 quad_perm:[1,0,3,2] row_mask:0xf bank_mask:0xf
	v_cndmask_b32_e32 v5, v7, v5, vcc
	v_cndmask_b32_e32 v6, v6, v7, vcc
	v_or_b32_e32 v7, 0xa000, v2
	s_waitcnt vmcnt(31)
	v_lshlrev_b32_e32 v10, 16, v95
	v_and_b32_e32 v9, 0xffff0000, v95
	v_mul_f32_e32 v5, v5, v10
	v_mul_f32_e32 v6, v6, v9
	v_cvt_pk_bf16_f32 v5, v5, v6
	global_store_dword v7, v5, s[44:45]
	v_mul_f32_e32 v5, v56, v1
	v_mul_f32_e32 v6, v57, v4
	v_cndmask_b32_e32 v9, v5, v6, vcc
	s_nop 1
	v_mov_b32_dpp v9, v9 quad_perm:[1,0,3,2] row_mask:0xf bank_mask:0xf
	v_cndmask_b32_e32 v5, v9, v5, vcc
	v_cndmask_b32_e32 v6, v6, v9, vcc
	s_waitcnt vmcnt(31)
	v_lshlrev_b32_e32 v10, 16, v96
	v_and_b32_e32 v9, 0xffff0000, v96
	v_mul_f32_e32 v5, v5, v10
	v_mul_f32_e32 v6, v6, v9
	v_cvt_pk_bf16_f32 v5, v5, v6
	global_store_dword v7, v5, s[44:45] offset:64
	v_mul_f32_e32 v5, v40, v1
	v_mul_f32_e32 v6, v41, v4
	v_cndmask_b32_e32 v9, v5, v6, vcc
	s_nop 1
	v_mov_b32_dpp v9, v9 quad_perm:[1,0,3,2] row_mask:0xf bank_mask:0xf
	v_mul_f32_e32 v1, v24, v1
	v_mul_f32_e32 v4, v25, v4
	v_cndmask_b32_e32 v5, v9, v5, vcc
	v_cndmask_b32_e32 v6, v6, v9, vcc
	s_waitcnt vmcnt(31)
	v_lshlrev_b32_e32 v10, 16, v97
	v_and_b32_e32 v9, 0xffff0000, v97
	v_mul_f32_e32 v5, v5, v10
	v_mul_f32_e32 v6, v6, v9
	v_cvt_pk_bf16_f32 v5, v5, v6
	global_store_dword v7, v5, s[44:45] offset:128
	v_cndmask_b32_e32 v5, v1, v4, vcc
	s_nop 1
	v_mov_b32_dpp v5, v5 quad_perm:[1,0,3,2] row_mask:0xf bank_mask:0xf
	v_cndmask_b32_e32 v1, v5, v1, vcc
	v_cndmask_b32_e32 v4, v4, v5, vcc
	s_waitcnt vmcnt(31)
	v_lshlrev_b32_e32 v6, 16, v98
	v_and_b32_e32 v5, 0xffff0000, v98
	v_mul_f32_e32 v1, v1, v6
	v_mul_f32_e32 v4, v4, v5
	v_cvt_pk_bf16_f32 v1, v1, v4
	global_store_dword v7, v1, s[44:45] offset:192
	ds_read_b128 v[4:7], v8 offset:64
	s_waitcnt lgkmcnt(0)
	v_rcp_f32_e32 v1, v4
	v_rcp_f32_e32 v4, v5
	v_mul_f32_e32 v5, v74, v1
	v_mul_f32_e32 v9, v75, v4
	v_cndmask_b32_e32 v10, v5, v9, vcc
	s_nop 1
	v_mov_b32_dpp v10, v10 quad_perm:[1,0,3,2] row_mask:0xf bank_mask:0xf
	v_cndmask_b32_e32 v5, v10, v5, vcc
	v_cndmask_b32_e32 v9, v9, v10, vcc
	v_or_b32_e32 v10, 0x10000, v2
	s_waitcnt vmcnt(31)
	v_lshlrev_b32_e32 v12, 16, v99
	v_and_b32_e32 v11, 0xffff0000, v99
	v_mul_f32_e32 v5, v5, v12
	v_mul_f32_e32 v9, v9, v11
	v_cvt_pk_bf16_f32 v5, v5, v9
	global_store_dword v10, v5, s[44:45]
	v_mul_f32_e32 v5, v58, v1
	v_mul_f32_e32 v9, v59, v4
	v_cndmask_b32_e32 v11, v5, v9, vcc
	s_nop 1
	v_mov_b32_dpp v11, v11 quad_perm:[1,0,3,2] row_mask:0xf bank_mask:0xf
	v_cndmask_b32_e32 v5, v11, v5, vcc
	v_cndmask_b32_e32 v9, v9, v11, vcc
	s_waitcnt vmcnt(31)
	v_lshlrev_b32_e32 v12, 16, v100
	v_and_b32_e32 v11, 0xffff0000, v100
	v_mul_f32_e32 v5, v5, v12
	v_mul_f32_e32 v9, v9, v11
	v_cvt_pk_bf16_f32 v5, v5, v9
	global_store_dword v10, v5, s[44:45] offset:64
	v_mul_f32_e32 v5, v42, v1
	v_mul_f32_e32 v9, v43, v4
	v_cndmask_b32_e32 v11, v5, v9, vcc
	s_nop 1
	v_mov_b32_dpp v11, v11 quad_perm:[1,0,3,2] row_mask:0xf bank_mask:0xf
	v_mul_f32_e32 v1, v26, v1
	v_mul_f32_e32 v4, v27, v4
	v_cndmask_b32_e32 v5, v11, v5, vcc
	v_cndmask_b32_e32 v9, v9, v11, vcc
	s_waitcnt vmcnt(31)
	v_lshlrev_b32_e32 v12, 16, v101
	v_and_b32_e32 v11, 0xffff0000, v101
	v_mul_f32_e32 v5, v5, v12
	v_mul_f32_e32 v9, v9, v11
	v_cvt_pk_bf16_f32 v5, v5, v9
	global_store_dword v10, v5, s[44:45] offset:128
	v_cndmask_b32_e32 v5, v1, v4, vcc
	s_nop 1
	v_mov_b32_dpp v5, v5 quad_perm:[1,0,3,2] row_mask:0xf bank_mask:0xf
	v_cndmask_b32_e32 v1, v5, v1, vcc
	v_cndmask_b32_e32 v4, v4, v5, vcc
	s_waitcnt vmcnt(31)
	v_lshlrev_b32_e32 v9, 16, v102
	v_and_b32_e32 v5, 0xffff0000, v102
	v_mul_f32_e32 v1, v1, v9
	v_mul_f32_e32 v4, v4, v5
	v_cvt_pk_bf16_f32 v1, v1, v4
	global_store_dword v10, v1, s[44:45] offset:192
	v_rcp_f32_e32 v1, v6
	v_rcp_f32_e32 v4, v7
	v_mul_f32_e32 v5, v76, v1
	v_mul_f32_e32 v6, v77, v4
	v_cndmask_b32_e32 v7, v5, v6, vcc
	s_nop 1
	v_mov_b32_dpp v7, v7 quad_perm:[1,0,3,2] row_mask:0xf bank_mask:0xf
	v_cndmask_b32_e32 v5, v7, v5, vcc
	v_cndmask_b32_e32 v6, v6, v7, vcc
	v_or_b32_e32 v7, 0x12000, v2
	s_waitcnt vmcnt(31)
	v_lshlrev_b32_e32 v10, 16, v103
	v_and_b32_e32 v9, 0xffff0000, v103
	v_mul_f32_e32 v5, v5, v10
	v_mul_f32_e32 v6, v6, v9
	v_cvt_pk_bf16_f32 v5, v5, v6
	global_store_dword v7, v5, s[44:45]
	v_mul_f32_e32 v5, v60, v1
	v_mul_f32_e32 v6, v61, v4
	v_cndmask_b32_e32 v9, v5, v6, vcc
	s_nop 1
	v_mov_b32_dpp v9, v9 quad_perm:[1,0,3,2] row_mask:0xf bank_mask:0xf
	v_cndmask_b32_e32 v5, v9, v5, vcc
	v_cndmask_b32_e32 v6, v6, v9, vcc
	s_waitcnt vmcnt(31)
	v_lshlrev_b32_e32 v10, 16, v104
	v_and_b32_e32 v9, 0xffff0000, v104
	v_mul_f32_e32 v5, v5, v10
	v_mul_f32_e32 v6, v6, v9
	v_cvt_pk_bf16_f32 v5, v5, v6
	global_store_dword v7, v5, s[44:45] offset:64
	v_mul_f32_e32 v5, v44, v1
	v_mul_f32_e32 v6, v45, v4
	v_cndmask_b32_e32 v9, v5, v6, vcc
	s_nop 1
	v_mov_b32_dpp v9, v9 quad_perm:[1,0,3,2] row_mask:0xf bank_mask:0xf
	v_mul_f32_e32 v1, v28, v1
	v_mul_f32_e32 v4, v29, v4
	v_cndmask_b32_e32 v5, v9, v5, vcc
	v_cndmask_b32_e32 v6, v6, v9, vcc
	s_waitcnt vmcnt(31)
	v_lshlrev_b32_e32 v10, 16, v105
	v_and_b32_e32 v9, 0xffff0000, v105
	v_mul_f32_e32 v5, v5, v10
	v_mul_f32_e32 v6, v6, v9
	v_cvt_pk_bf16_f32 v5, v5, v6
	global_store_dword v7, v5, s[44:45] offset:128
	v_cndmask_b32_e32 v5, v1, v4, vcc
	s_nop 1
	v_mov_b32_dpp v5, v5 quad_perm:[1,0,3,2] row_mask:0xf bank_mask:0xf
	v_cndmask_b32_e32 v1, v5, v1, vcc
	v_cndmask_b32_e32 v4, v4, v5, vcc
	s_waitcnt vmcnt(31)
	v_lshlrev_b32_e32 v6, 16, v106
	v_and_b32_e32 v5, 0xffff0000, v106
	v_mul_f32_e32 v1, v1, v6
	v_mul_f32_e32 v4, v4, v5
	v_cvt_pk_bf16_f32 v1, v1, v4
	global_store_dword v7, v1, s[44:45] offset:192
	ds_read_b128 v[4:7], v8 offset:96
	s_waitcnt lgkmcnt(0)
	v_rcp_f32_e32 v4, v4
	v_rcp_f32_e32 v5, v5
	v_mul_f32_e32 v1, v78, v4
	v_mul_f32_e32 v8, v79, v5
	v_cndmask_b32_e32 v9, v1, v8, vcc
	s_nop 1
	v_mov_b32_dpp v9, v9 quad_perm:[1,0,3,2] row_mask:0xf bank_mask:0xf
	v_cndmask_b32_e32 v1, v9, v1, vcc
	v_cndmask_b32_e32 v8, v8, v9, vcc
	v_or_b32_e32 v9, 0x18000, v2
	v_or_b32_e32 v2, 0x1a000, v2
	s_waitcnt vmcnt(31)
	v_lshlrev_b32_e32 v11, 16, v107
	v_and_b32_e32 v10, 0xffff0000, v107
	v_mul_f32_e32 v1, v1, v11
	v_mul_f32_e32 v8, v8, v10
	v_cvt_pk_bf16_f32 v1, v1, v8
	global_store_dword v9, v1, s[44:45]
	v_mul_f32_e32 v1, v62, v4
	v_mul_f32_e32 v8, v63, v5
	v_cndmask_b32_e32 v10, v1, v8, vcc
	s_nop 1
	v_mov_b32_dpp v10, v10 quad_perm:[1,0,3,2] row_mask:0xf bank_mask:0xf
	v_cndmask_b32_e32 v1, v10, v1, vcc
	v_cndmask_b32_e32 v8, v8, v10, vcc
	s_waitcnt vmcnt(31)
	v_lshlrev_b32_e32 v11, 16, v108
	v_and_b32_e32 v10, 0xffff0000, v108
	v_mul_f32_e32 v1, v1, v11
	v_mul_f32_e32 v8, v8, v10
	v_cvt_pk_bf16_f32 v1, v1, v8
	global_store_dword v9, v1, s[44:45] offset:64
	v_mul_f32_e32 v1, v46, v4
	v_mul_f32_e32 v8, v47, v5
	v_cndmask_b32_e32 v10, v1, v8, vcc
	s_nop 1
	v_mov_b32_dpp v10, v10 quad_perm:[1,0,3,2] row_mask:0xf bank_mask:0xf
	v_cndmask_b32_e32 v1, v10, v1, vcc
	v_cndmask_b32_e32 v8, v8, v10, vcc
	s_waitcnt vmcnt(31)
	v_lshlrev_b32_e32 v11, 16, v109
	v_and_b32_e32 v10, 0xffff0000, v109
	v_mul_f32_e32 v1, v1, v11
	v_mul_f32_e32 v8, v8, v10
	v_cvt_pk_bf16_f32 v1, v1, v8
	global_store_dword v9, v1, s[44:45] offset:128
	v_mul_f32_e32 v1, v30, v4
	v_mul_f32_e32 v4, v31, v5
	v_cndmask_b32_e32 v5, v1, v4, vcc
	s_nop 1
	v_mov_b32_dpp v5, v5 quad_perm:[1,0,3,2] row_mask:0xf bank_mask:0xf
	v_cndmask_b32_e32 v1, v5, v1, vcc
	v_cndmask_b32_e32 v4, v4, v5, vcc
	s_waitcnt vmcnt(31)
	v_lshlrev_b32_e32 v8, 16, v110
	v_and_b32_e32 v5, 0xffff0000, v110
	v_mul_f32_e32 v1, v1, v8
	v_mul_f32_e32 v4, v4, v5
	v_cvt_pk_bf16_f32 v1, v1, v4
	global_store_dword v9, v1, s[44:45] offset:192
	v_rcp_f32_e32 v1, v6
	v_rcp_f32_e32 v4, v7
	v_mul_f32_e32 v5, v80, v1
	v_mul_f32_e32 v6, v81, v4
	v_cndmask_b32_e32 v7, v5, v6, vcc
	s_nop 1
	v_mov_b32_dpp v7, v7 quad_perm:[1,0,3,2] row_mask:0xf bank_mask:0xf
	v_cndmask_b32_e32 v5, v7, v5, vcc
	v_cndmask_b32_e32 v6, v6, v7, vcc
	s_waitcnt vmcnt(31)
	v_lshlrev_b32_e32 v8, 16, v111
	v_and_b32_e32 v7, 0xffff0000, v111
	v_mul_f32_e32 v5, v5, v8
	v_mul_f32_e32 v6, v6, v7
	v_cvt_pk_bf16_f32 v5, v5, v6
	global_store_dword v2, v5, s[44:45]
	v_mul_f32_e32 v5, v64, v1
	v_mul_f32_e32 v6, v65, v4
	v_cndmask_b32_e32 v7, v5, v6, vcc
	s_nop 1
	v_mov_b32_dpp v7, v7 quad_perm:[1,0,3,2] row_mask:0xf bank_mask:0xf
	v_cndmask_b32_e32 v5, v7, v5, vcc
	v_cndmask_b32_e32 v6, v6, v7, vcc
	s_waitcnt vmcnt(31)
	v_lshlrev_b32_e32 v8, 16, v112
	v_and_b32_e32 v7, 0xffff0000, v112
	v_mul_f32_e32 v5, v5, v8
	v_mul_f32_e32 v6, v6, v7
	v_cvt_pk_bf16_f32 v5, v5, v6
	global_store_dword v2, v5, s[44:45] offset:64
	v_mul_f32_e32 v5, v48, v1
	v_mul_f32_e32 v6, v49, v4
	v_cndmask_b32_e32 v7, v5, v6, vcc
	s_nop 1
	v_mov_b32_dpp v7, v7 quad_perm:[1,0,3,2] row_mask:0xf bank_mask:0xf
	v_mul_f32_e32 v1, v32, v1
	v_mul_f32_e32 v4, v33, v4
	v_cndmask_b32_e32 v5, v7, v5, vcc
	v_cndmask_b32_e32 v6, v6, v7, vcc
	s_waitcnt vmcnt(31)
	v_lshlrev_b32_e32 v8, 16, v113
	v_and_b32_e32 v7, 0xffff0000, v113
	v_mul_f32_e32 v5, v5, v8
	v_mul_f32_e32 v6, v6, v7
	v_cvt_pk_bf16_f32 v5, v5, v6
	global_store_dword v2, v5, s[44:45] offset:128
	v_cndmask_b32_e32 v5, v1, v4, vcc
	s_nop 1
	v_mov_b32_dpp v5, v5 quad_perm:[1,0,3,2] row_mask:0xf bank_mask:0xf
	v_cndmask_b32_e32 v1, v5, v1, vcc
	v_cndmask_b32_e32 v4, v4, v5, vcc
	s_waitcnt vmcnt(31)
	v_lshlrev_b32_e32 v6, 16, v114
	v_and_b32_e32 v5, 0xffff0000, v114
	v_mul_f32_e32 v1, v1, v6
	v_mul_f32_e32 v4, v4, v5
	v_cvt_pk_bf16_f32 v1, v1, v4
	global_store_dword v2, v1, s[44:45] offset:192
	s_mov_b64 s[44:45], 0
